# GEMM K-loop: removed the redundant s_setprio 0 / s_setprio 1 pair sitting between MFMA 16 and 17 of each 32-MFMA cluster (two fewer issue slots in the MFMA-paced segment)
# speedup vs baseline: 1.0043x; 1.0017x over previous
; #define PG8_STAGE(bufoff, gbase, voff) do { _Pragma("unroll") for (int _i = 0; _i < 2; ++_i) \
;         __builtin_amdgcn_global_load_lds((const unsigned*)((const char*)(gbase) + (voff)[_i]), (PG8_LAS unsigned*)(lds + (bufoff) + ldsw + _i * 8192), 16, 0, 0); } while (0)
; #define PG8_LDA(dst, b, h) do { _Pragma("unroll") for (int m = 0; m < 4; ++m) _Pragma("unroll") for (int k = 0; k < 2; ++k) dst[m][k] = *(const PG8_LAS bf16x8*)(lds + PG8_SA(b, h) + aoff + m * 2048 + k * 1024); } while (0)
; #define PG8_LDB(dst, b, h) do { _Pragma("unroll") for (int n = 0; n < 2; ++n) _Pragma("unroll") for (int k = 0; k < 2; ++k) dst[n][k] = *(const PG8_LAS bf16x8*)(lds + PG8_SB(b, h) + boff + n * 2048 + k * 1024); } while (0)
; #define PG8_MMA(ai, bj, At, Bt) do { __builtin_amdgcn_s_setprio(1); _Pragma("unroll") for (int m = 0; m < 4; ++m) _Pragma("unroll") for (int n = 0; n < 2; ++n) _Pragma("unroll") for (int k = 0; k < 2; ++k) \
;         acc[ai][bj][m][n] = __builtin_amdgcn_mfma_f32_16x16x32_bf16(Bt[n][k], At[m][k], acc[ai][bj][m][n], 0, 0, 0); __builtin_amdgcn_s_setprio(0); } while (0)
; #define PG8_WAIT_V(n) asm volatile("s_waitcnt vmcnt(" #n ")" ::: "memory")
; #define PG8_WAIT_L(n) asm volatile("s_waitcnt lgkmcnt(" #n ")" ::: "memory")
; #define PG8_BAR __builtin_amdgcn_s_barrier()
; #define PG8_SCHED __builtin_amdgcn_sched_barrier(0)
; template <class Epi, class Sched, bool ALIGN_EPI = false, bool SP2 = false>
; __device__ __forceinline__ void gemm_phase(PG8_LAS unsigned char* lds, const Gemm g, const Sched& S, const Epi& E) {
;     ...
;             PG8_LDB(B0, 0, 0); PG8_LDB(B1, 0, 1); PG8_SCHED; PG8_LDA(At, 0, 0); PG8_STAGE(PG8_SA(1, 1), a1 + hstep, voffA);
;             PG8_WAIT_V(8); PG8_WAIT_L(0); PG8_BAR; PG8_MMA(0, 0, At, B0); PG8_MMA(0, 1, At, B1); PG8_BAR; PG8_SCHED;
;             PG8_LDA(At, 0, 1); PG8_STAGE(PG8_SB(0, 0), b2, voffB); PG8_STAGE(PG8_SB(0, 1), b2 + hstep, voffB); PG8_STAGE(PG8_SA(0, 0), a2, voffA);
;             PG8_WAIT_V(8); PG8_WAIT_L(0); PG8_BAR; PG8_MMA(1, 0, At, B0); PG8_MMA(1, 1, At, B1); PG8_BAR; PG8_SCHED;
.LBB0_154:
	s_add_i32 s18, s14, 2
	s_add_u32 s19, s12, 0x80
	s_addc_u32 s15, s13, 0
	s_add_i32 s24, 0, 0x10000
	s_cmp_eq_u32 s91, s14
	s_cselect_b32 s15, s7, s15
	s_cselect_b32 s14, s6, s19
	v_add_u32_e32 v156, s24, v159
	s_cselect_b32 s23, s9, s11
	s_cselect_b32 s22, s8, s2
	s_add_i32 s19, 0, 0x14000
	ds_read_b128 v[170:173], v156
	ds_read_b128 v[174:177], v156 offset:1024
	ds_read_b128 v[178:181], v156 offset:2048
	ds_read_b128 v[192:195], v156 offset:3072
	v_add_u32_e32 v156, s19, v159
	ds_read_b128 v[196:199], v156
	ds_read_b128 v[200:203], v156 offset:1024
	ds_read_b128 v[204:207], v156 offset:2048
	ds_read_b128 v[208:211], v156 offset:3072
	v_lshl_add_u64 v[156:157], s[12:13], 0, v[152:153]
	s_add_i32 m0, s82, 0xc000
	ds_read_b128 v[212:215], v168
	ds_read_b128 v[216:219], v168 offset:1024
	ds_read_b128 v[220:223], v168 offset:2048
	ds_read_b128 v[224:227], v168 offset:3072
	ds_read_b128 v[228:231], v168 offset:4096
	ds_read_b128 v[232:235], v168 offset:5120
	ds_read_b128 v[236:239], v168 offset:6144
	ds_read_b128 v[240:243], v168 offset:7168
	global_load_lds_dwordx4 v[156:157], off
	v_lshl_add_u64 v[156:157], s[12:13], 0, v[154:155]
	s_add_i32 m0, s82, 0xe000
	s_nop 0
	global_load_lds_dwordx4 v[156:157], off
	s_waitcnt vmcnt(8)
	s_waitcnt lgkmcnt(0)
	s_barrier
	s_setprio 1
	s_waitcnt lgkmcnt(0)
	v_mfma_f32_16x16x32_bf16 v[126:129], v[170:173], v[212:215], v[126:129]
	v_mfma_f32_16x16x32_bf16 v[122:125], v[178:181], v[212:215], v[122:125]
	v_mfma_f32_16x16x32_bf16 v[118:121], v[170:173], v[220:223], v[118:121]
	v_mfma_f32_16x16x32_bf16 v[114:117], v[178:181], v[220:223], v[114:117]
	v_mfma_f32_16x16x32_bf16 v[110:113], v[170:173], v[228:231], v[110:113]
	v_mfma_f32_16x16x32_bf16 v[106:109], v[178:181], v[228:231], v[106:109]
	v_mfma_f32_16x16x32_bf16 v[102:105], v[170:173], v[236:239], v[102:105]
	v_mfma_f32_16x16x32_bf16 v[98:101], v[178:181], v[236:239], v[98:101]
	v_mfma_f32_16x16x32_bf16 v[126:129], v[174:177], v[216:219], v[126:129]
	v_mfma_f32_16x16x32_bf16 v[122:125], v[192:195], v[216:219], v[122:125]
	v_mfma_f32_16x16x32_bf16 v[118:121], v[174:177], v[224:227], v[118:121]
	v_mfma_f32_16x16x32_bf16 v[114:117], v[192:195], v[224:227], v[114:117]
	v_mfma_f32_16x16x32_bf16 v[110:113], v[174:177], v[232:235], v[110:113]
	v_mfma_f32_16x16x32_bf16 v[106:109], v[192:195], v[232:235], v[106:109]
	v_mfma_f32_16x16x32_bf16 v[102:105], v[174:177], v[240:243], v[102:105]
	v_mfma_f32_16x16x32_bf16 v[98:101], v[192:195], v[240:243], v[98:101]
	v_mfma_f32_16x16x32_bf16 v[62:65], v[196:199], v[212:215], v[62:65]
	v_mfma_f32_16x16x32_bf16 v[58:61], v[204:207], v[212:215], v[58:61]
	v_mfma_f32_16x16x32_bf16 v[54:57], v[196:199], v[220:223], v[54:57]
	v_mfma_f32_16x16x32_bf16 v[50:53], v[204:207], v[220:223], v[50:53]
	v_mfma_f32_16x16x32_bf16 v[46:49], v[196:199], v[228:231], v[46:49]
	v_mfma_f32_16x16x32_bf16 v[42:45], v[204:207], v[228:231], v[42:45]
	v_mfma_f32_16x16x32_bf16 v[38:41], v[196:199], v[236:239], v[38:41]
	v_mfma_f32_16x16x32_bf16 v[34:37], v[204:207], v[236:239], v[34:37]
	v_mfma_f32_16x16x32_bf16 v[62:65], v[200:203], v[216:219], v[62:65]
	v_mfma_f32_16x16x32_bf16 v[58:61], v[208:211], v[216:219], v[58:61]
	v_mfma_f32_16x16x32_bf16 v[54:57], v[200:203], v[224:227], v[54:57]
	v_mfma_f32_16x16x32_bf16 v[50:53], v[208:211], v[224:227], v[50:53]
	v_mfma_f32_16x16x32_bf16 v[46:49], v[200:203], v[232:235], v[46:49]
	v_mfma_f32_16x16x32_bf16 v[42:45], v[208:211], v[232:235], v[42:45]
	v_mfma_f32_16x16x32_bf16 v[38:41], v[200:203], v[240:243], v[38:41]
	v_mfma_f32_16x16x32_bf16 v[34:37], v[208:211], v[240:243], v[34:37]
	s_setprio 0
	s_barrier
	s_add_i32 s24, s24, s69
	v_lshl_add_u64 v[156:157], s[22:23], 0, v[0:1]
	s_mov_b32 m0, s24
	ds_read_b128 v[212:215], v168 offset:16384
	ds_read_b128 v[216:219], v168 offset:17408
	ds_read_b128 v[220:223], v168 offset:18432
	ds_read_b128 v[224:227], v168 offset:19456
	ds_read_b128 v[228:231], v168 offset:20480
	ds_read_b128 v[232:235], v168 offset:21504
	ds_read_b128 v[236:239], v168 offset:22528
	ds_read_b128 v[240:243], v168 offset:23552
	global_load_lds_dwordx4 v[156:157], off
	s_add_i32 m0, s24, 0x2000
	v_lshl_add_u64 v[182:183], s[22:23], 0, v[134:135]
	s_add_u32 s22, s22, s78
	s_addc_u32 s23, s23, 0
	s_add_i32 s19, s19, s69
	global_load_lds_dwordx4 v[182:183], off
	v_lshl_add_u64 v[244:245], s[22:23], 0, v[0:1]
	s_mov_b32 m0, s19
	v_lshl_add_u64 v[246:247], s[22:23], 0, v[134:135]
	global_load_lds_dwordx4 v[244:245], off
	s_add_i32 m0, s19, 0x2000
	v_lshl_add_u64 v[248:249], s[14:15], 0, v[130:131]
	global_load_lds_dwordx4 v[246:247], off
	s_mov_b32 m0, s82
	v_lshl_add_u64 v[250:251], s[14:15], 0, v[132:133]
	global_load_lds_dwordx4 v[248:249], off
	s_mov_b32 m0, s66
	s_nop 0
	global_load_lds_dwordx4 v[250:251], off
	s_waitcnt vmcnt(8)
	s_waitcnt lgkmcnt(0)
	s_barrier
; #define PG8_STAGE(bufoff, gbase, voff) do { _Pragma("unroll") for (int _i = 0; _i < 2; ++_i) \
;         __builtin_amdgcn_global_load_lds((const unsigned*)((const char*)(gbase) + (voff)[_i]), (PG8_LAS unsigned*)(lds + (bufoff) + ldsw + _i * 8192), 16, 0, 0); } while (0)
; #define PG8_LDA(dst, b, h) do { _Pragma("unroll") for (int m = 0; m < 4; ++m) _Pragma("unroll") for (int k = 0; k < 2; ++k) dst[m][k] = *(const PG8_LAS bf16x8*)(lds + PG8_SA(b, h) + aoff + m * 2048 + k * 1024); } while (0)
; #define PG8_LDB(dst, b, h) do { _Pragma("unroll") for (int n = 0; n < 2; ++n) _Pragma("unroll") for (int k = 0; k < 2; ++k) dst[n][k] = *(const PG8_LAS bf16x8*)(lds + PG8_SB(b, h) + boff + n * 2048 + k * 1024); } while (0)
; #define PG8_MMA(ai, bj, At, Bt) do { __builtin_amdgcn_s_setprio(1); _Pragma("unroll") for (int m = 0; m < 4; ++m) _Pragma("unroll") for (int n = 0; n < 2; ++n) _Pragma("unroll") for (int k = 0; k < 2; ++k) \
;         acc[ai][bj][m][n] = __builtin_amdgcn_mfma_f32_16x16x32_bf16(Bt[n][k], At[m][k], acc[ai][bj][m][n], 0, 0, 0); __builtin_amdgcn_s_setprio(0); } while (0)
; #define PG8_WAIT_V(n) asm volatile("s_waitcnt vmcnt(" #n ")" ::: "memory")
; #define PG8_WAIT_L(n) asm volatile("s_waitcnt lgkmcnt(" #n ")" ::: "memory")
; #define PG8_BAR __builtin_amdgcn_s_barrier()
; #define PG8_SCHED __builtin_amdgcn_sched_barrier(0)
; template <class Epi, class Sched, bool ALIGN_EPI = false, bool SP2 = false>
; __device__ __forceinline__ void gemm_phase(PG8_LAS unsigned char* lds, const Gemm g, const Sched& S, const Epi& E) {
;     ...
;             PG8_WAIT_V(8); PG8_WAIT_L(0); PG8_BAR; PG8_MMA(1, 0, At, B0); PG8_MMA(1, 1, At, B1); PG8_BAR; PG8_SCHED;
;             PG8_LDB(B0, 1, 0); PG8_LDB(B1, 1, 1); PG8_SCHED; PG8_LDA(At, 1, 0); PG8_STAGE(PG8_SA(0, 1), a2 + hstep, voffA);
;             PG8_WAIT_V(8); PG8_WAIT_L(0); PG8_BAR; PG8_MMA(0, 0, At, B0); PG8_MMA(0, 1, At, B1); PG8_BAR; PG8_SCHED;
	s_setprio 1
	s_waitcnt lgkmcnt(0)
	v_mfma_f32_16x16x32_bf16 v[94:97], v[170:173], v[212:215], v[94:97]
	v_mfma_f32_16x16x32_bf16 v[90:93], v[178:181], v[212:215], v[90:93]
	v_mfma_f32_16x16x32_bf16 v[86:89], v[170:173], v[220:223], v[86:89]
	v_mfma_f32_16x16x32_bf16 v[82:85], v[178:181], v[220:223], v[82:85]
	v_mfma_f32_16x16x32_bf16 v[78:81], v[170:173], v[228:231], v[78:81]
	v_mfma_f32_16x16x32_bf16 v[74:77], v[178:181], v[228:231], v[74:77]
	v_mfma_f32_16x16x32_bf16 v[70:73], v[170:173], v[236:239], v[70:73]
	v_mfma_f32_16x16x32_bf16 v[66:69], v[178:181], v[236:239], v[66:69]
	v_mfma_f32_16x16x32_bf16 v[94:97], v[174:177], v[216:219], v[94:97]
	v_mfma_f32_16x16x32_bf16 v[90:93], v[192:195], v[216:219], v[90:93]
	v_mfma_f32_16x16x32_bf16 v[86:89], v[174:177], v[224:227], v[86:89]
	v_mfma_f32_16x16x32_bf16 v[82:85], v[192:195], v[224:227], v[82:85]
	v_mfma_f32_16x16x32_bf16 v[78:81], v[174:177], v[232:235], v[78:81]
	v_mfma_f32_16x16x32_bf16 v[74:77], v[192:195], v[232:235], v[74:77]
	v_mfma_f32_16x16x32_bf16 v[70:73], v[174:177], v[240:243], v[70:73]
	v_mfma_f32_16x16x32_bf16 v[66:69], v[192:195], v[240:243], v[66:69]
	v_mfma_f32_16x16x32_bf16 v[30:33], v[196:199], v[212:215], v[30:33]
	v_mfma_f32_16x16x32_bf16 v[26:29], v[204:207], v[212:215], v[26:29]
	v_mfma_f32_16x16x32_bf16 v[22:25], v[196:199], v[220:223], v[22:25]
	v_mfma_f32_16x16x32_bf16 v[18:21], v[204:207], v[220:223], v[18:21]
	v_mfma_f32_16x16x32_bf16 v[14:17], v[196:199], v[228:231], v[14:17]
	v_mfma_f32_16x16x32_bf16 v[10:13], v[204:207], v[228:231], v[10:13]
	v_mfma_f32_16x16x32_bf16 v[6:9], v[196:199], v[236:239], v[6:9]
	v_mfma_f32_16x16x32_bf16 v[2:5], v[204:207], v[236:239], v[2:5]
	v_mfma_f32_16x16x32_bf16 v[30:33], v[200:203], v[216:219], v[30:33]
	v_mfma_f32_16x16x32_bf16 v[26:29], v[208:211], v[216:219], v[26:29]
	v_mfma_f32_16x16x32_bf16 v[22:25], v[200:203], v[224:227], v[22:25]
	v_mfma_f32_16x16x32_bf16 v[18:21], v[208:211], v[224:227], v[18:21]
	v_mfma_f32_16x16x32_bf16 v[14:17], v[200:203], v[232:235], v[14:17]
	v_mfma_f32_16x16x32_bf16 v[10:13], v[208:211], v[232:235], v[10:13]
	v_mfma_f32_16x16x32_bf16 v[6:9], v[200:203], v[240:243], v[6:9]
	v_mfma_f32_16x16x32_bf16 v[2:5], v[208:211], v[240:243], v[2:5]
	s_setprio 0
	s_barrier
	s_add_i32 s19, 0, 0x18000
	v_add_u32_e32 v169, s19, v159
	s_add_i32 s22, 0, 0x1c000
	ds_read_b128 v[170:173], v169
	ds_read_b128 v[174:177], v169 offset:1024
	ds_read_b128 v[178:181], v169 offset:2048
	ds_read_b128 v[192:195], v169 offset:3072
	v_add_u32_e32 v169, s22, v159
	ds_read_b128 v[196:199], v169
	ds_read_b128 v[200:203], v169 offset:1024
	ds_read_b128 v[204:207], v169 offset:2048
	ds_read_b128 v[208:211], v169 offset:3072
	s_add_u32 s14, s14, s78
	s_addc_u32 s15, s15, 0
	s_mov_b32 m0, s67
	v_lshl_add_u64 v[252:253], s[14:15], 0, v[130:131]
	ds_read_b128 v[212:215], v168 offset:32768
	ds_read_b128 v[216:219], v168 offset:33792
	ds_read_b128 v[220:223], v168 offset:34816
	ds_read_b128 v[224:227], v168 offset:35840
	ds_read_b128 v[228:231], v168 offset:36864
	ds_read_b128 v[232:235], v168 offset:37888
	ds_read_b128 v[236:239], v168 offset:38912
	ds_read_b128 v[240:243], v168 offset:39936
	global_load_lds_dwordx4 v[252:253], off
	v_lshl_add_u64 v[252:253], s[14:15], 0, v[132:133]
	s_mov_b32 m0, s45
	s_nop 0
	global_load_lds_dwordx4 v[252:253], off
	s_waitcnt vmcnt(8)
	s_waitcnt lgkmcnt(0)
	s_barrier
	s_setprio 1
	s_waitcnt lgkmcnt(0)
	v_mfma_f32_16x16x32_bf16 v[126:129], v[170:173], v[212:215], v[126:129]
	v_mfma_f32_16x16x32_bf16 v[122:125], v[178:181], v[212:215], v[122:125]
	v_mfma_f32_16x16x32_bf16 v[118:121], v[170:173], v[220:223], v[118:121]
	v_mfma_f32_16x16x32_bf16 v[114:117], v[178:181], v[220:223], v[114:117]
	v_mfma_f32_16x16x32_bf16 v[110:113], v[170:173], v[228:231], v[110:113]
	v_mfma_f32_16x16x32_bf16 v[106:109], v[178:181], v[228:231], v[106:109]
	v_mfma_f32_16x16x32_bf16 v[102:105], v[170:173], v[236:239], v[102:105]
	v_mfma_f32_16x16x32_bf16 v[98:101], v[178:181], v[236:239], v[98:101]
	v_mfma_f32_16x16x32_bf16 v[126:129], v[174:177], v[216:219], v[126:129]
	v_mfma_f32_16x16x32_bf16 v[122:125], v[192:195], v[216:219], v[122:125]
	v_mfma_f32_16x16x32_bf16 v[118:121], v[174:177], v[224:227], v[118:121]
	v_mfma_f32_16x16x32_bf16 v[114:117], v[192:195], v[224:227], v[114:117]
	v_mfma_f32_16x16x32_bf16 v[110:113], v[174:177], v[232:235], v[110:113]
	v_mfma_f32_16x16x32_bf16 v[106:109], v[192:195], v[232:235], v[106:109]
	v_mfma_f32_16x16x32_bf16 v[102:105], v[174:177], v[240:243], v[102:105]
	v_mfma_f32_16x16x32_bf16 v[98:101], v[192:195], v[240:243], v[98:101]
	v_mfma_f32_16x16x32_bf16 v[62:65], v[196:199], v[212:215], v[62:65]
	v_mfma_f32_16x16x32_bf16 v[58:61], v[204:207], v[212:215], v[58:61]
	v_mfma_f32_16x16x32_bf16 v[54:57], v[196:199], v[220:223], v[54:57]
	v_mfma_f32_16x16x32_bf16 v[50:53], v[204:207], v[220:223], v[50:53]
	v_mfma_f32_16x16x32_bf16 v[46:49], v[196:199], v[228:231], v[46:49]
	v_mfma_f32_16x16x32_bf16 v[42:45], v[204:207], v[228:231], v[42:45]
	v_mfma_f32_16x16x32_bf16 v[38:41], v[196:199], v[236:239], v[38:41]
	v_mfma_f32_16x16x32_bf16 v[34:37], v[204:207], v[236:239], v[34:37]
	v_mfma_f32_16x16x32_bf16 v[62:65], v[200:203], v[216:219], v[62:65]
	v_mfma_f32_16x16x32_bf16 v[58:61], v[208:211], v[216:219], v[58:61]
	v_mfma_f32_16x16x32_bf16 v[54:57], v[200:203], v[224:227], v[54:57]
	v_mfma_f32_16x16x32_bf16 v[50:53], v[208:211], v[224:227], v[50:53]
	v_mfma_f32_16x16x32_bf16 v[46:49], v[200:203], v[232:235], v[46:49]
	v_mfma_f32_16x16x32_bf16 v[42:45], v[208:211], v[232:235], v[42:45]
	v_mfma_f32_16x16x32_bf16 v[38:41], v[200:203], v[240:243], v[38:41]
	v_mfma_f32_16x16x32_bf16 v[34:37], v[208:211], v[240:243], v[34:37]
	s_setprio 0
	s_barrier
; #define PG8_STAGE(bufoff, gbase, voff) do { _Pragma("unroll") for (int _i = 0; _i < 2; ++_i) \
;         __builtin_amdgcn_global_load_lds((const unsigned*)((const char*)(gbase) + (voff)[_i]), (PG8_LAS unsigned*)(lds + (bufoff) + ldsw + _i * 8192), 16, 0, 0); } while (0)
; #define PG8_LDA(dst, b, h) do { _Pragma("unroll") for (int m = 0; m < 4; ++m) _Pragma("unroll") for (int k = 0; k < 2; ++k) dst[m][k] = *(const PG8_LAS bf16x8*)(lds + PG8_SA(b, h) + aoff + m * 2048 + k * 1024); } while (0)
; #define PG8_MMA(ai, bj, At, Bt) do { __builtin_amdgcn_s_setprio(1); _Pragma("unroll") for (int m = 0; m < 4; ++m) _Pragma("unroll") for (int n = 0; n < 2; ++n) _Pragma("unroll") for (int k = 0; k < 2; ++k) \
;         acc[ai][bj][m][n] = __builtin_amdgcn_mfma_f32_16x16x32_bf16(Bt[n][k], At[m][k], acc[ai][bj][m][n], 0, 0, 0); __builtin_amdgcn_s_setprio(0); } while (0)
; #define PG8_WAIT_V(n) asm volatile("s_waitcnt vmcnt(" #n ")" ::: "memory")
; #define PG8_WAIT_L(n) asm volatile("s_waitcnt lgkmcnt(" #n ")" ::: "memory")
; #define PG8_BAR __builtin_amdgcn_s_barrier()
; #define PG8_SCHED __builtin_amdgcn_sched_barrier(0)
; template <class Epi, class Sched, bool ALIGN_EPI = false, bool SP2 = false>
; __device__ __forceinline__ void gemm_phase(PG8_LAS unsigned char* lds, const Gemm g, const Sched& S, const Epi& E) {
;     ...
;         for (int t = 0; t < nt; t += 2) {
;             const bool last = (t == nt - 2);
;             const char* a1 = cA + (size_t)(t + 1) * kstep;
;             const char* a2 = last ? nA : cA + (size_t)(t + 2) * kstep; const char* b2 = last ? nB : cB + (size_t)(t + 2) * kstep;
;     ...
;             PG8_LDA(At, 1, 1); PG8_STAGE(PG8_SB(1, 0), b3, voffB); PG8_STAGE(PG8_SB(1, 1), b3 + hstep, voffB); PG8_STAGE(PG8_SA(1, 0), a3, voffA);
;             PG8_WAIT_V(8); PG8_WAIT_L(0); PG8_BAR; PG8_MMA(1, 0, At, B0); PG8_MMA(1, 1, At, B1); PG8_BAR; PG8_SCHED;
	s_add_i32 s14, s19, s69
	v_lshl_add_u64 v[156:157], v[156:157], 0, s[92:93]
	s_mov_b32 m0, s14
	ds_read_b128 v[212:215], v168 offset:49152
	ds_read_b128 v[216:219], v168 offset:50176
	ds_read_b128 v[220:223], v168 offset:51200
	ds_read_b128 v[224:227], v168 offset:52224
	ds_read_b128 v[228:231], v168 offset:53248
	ds_read_b128 v[232:235], v168 offset:54272
	ds_read_b128 v[236:239], v168 offset:55296
	ds_read_b128 v[240:243], v168 offset:56320
	global_load_lds_dwordx4 v[156:157], off
	v_lshl_add_u64 v[156:157], v[182:183], 0, s[92:93]
	s_add_i32 m0, s14, 0x2000
	s_add_i32 s14, s22, s69
	global_load_lds_dwordx4 v[156:157], off
	v_lshl_add_u64 v[156:157], v[244:245], 0, s[92:93]
	s_mov_b32 m0, s14
	s_nop 0
	global_load_lds_dwordx4 v[156:157], off
	v_lshl_add_u64 v[156:157], v[246:247], 0, s[92:93]
	s_add_i32 m0, s14, 0x2000
	s_nop 0
	global_load_lds_dwordx4 v[156:157], off
	v_lshl_add_u64 v[156:157], v[248:249], 0, s[92:93]
	s_mov_b32 m0, s36
	s_nop 0
	global_load_lds_dwordx4 v[156:157], off
	v_lshl_add_u64 v[156:157], v[250:251], 0, s[92:93]
	s_mov_b32 m0, s35
	s_nop 0
	global_load_lds_dwordx4 v[156:157], off
	s_waitcnt vmcnt(8)
	s_waitcnt lgkmcnt(0)
	s_barrier
	s_setprio 1
	s_waitcnt lgkmcnt(0)
	v_mfma_f32_16x16x32_bf16 v[94:97], v[170:173], v[212:215], v[94:97]
	v_mfma_f32_16x16x32_bf16 v[90:93], v[178:181], v[212:215], v[90:93]
	v_mfma_f32_16x16x32_bf16 v[86:89], v[170:173], v[220:223], v[86:89]
	v_mfma_f32_16x16x32_bf16 v[82:85], v[178:181], v[220:223], v[82:85]
	v_mfma_f32_16x16x32_bf16 v[78:81], v[170:173], v[228:231], v[78:81]
	v_mfma_f32_16x16x32_bf16 v[74:77], v[178:181], v[228:231], v[74:77]
	v_mfma_f32_16x16x32_bf16 v[70:73], v[170:173], v[236:239], v[70:73]
	v_mfma_f32_16x16x32_bf16 v[66:69], v[178:181], v[236:239], v[66:69]
	v_mfma_f32_16x16x32_bf16 v[94:97], v[174:177], v[216:219], v[94:97]
	v_mfma_f32_16x16x32_bf16 v[90:93], v[192:195], v[216:219], v[90:93]
	v_mfma_f32_16x16x32_bf16 v[86:89], v[174:177], v[224:227], v[86:89]
	v_mfma_f32_16x16x32_bf16 v[82:85], v[192:195], v[224:227], v[82:85]
	v_mfma_f32_16x16x32_bf16 v[78:81], v[174:177], v[232:235], v[78:81]
	v_mfma_f32_16x16x32_bf16 v[74:77], v[192:195], v[232:235], v[74:77]
	v_mfma_f32_16x16x32_bf16 v[70:73], v[174:177], v[240:243], v[70:73]
	v_mfma_f32_16x16x32_bf16 v[66:69], v[192:195], v[240:243], v[66:69]
	v_mfma_f32_16x16x32_bf16 v[30:33], v[196:199], v[212:215], v[30:33]
	v_mfma_f32_16x16x32_bf16 v[26:29], v[204:207], v[212:215], v[26:29]
	v_mfma_f32_16x16x32_bf16 v[22:25], v[196:199], v[220:223], v[22:25]
	v_mfma_f32_16x16x32_bf16 v[18:21], v[204:207], v[220:223], v[18:21]
	v_mfma_f32_16x16x32_bf16 v[14:17], v[196:199], v[228:231], v[14:17]
	v_mfma_f32_16x16x32_bf16 v[10:13], v[204:207], v[228:231], v[10:13]
	v_mfma_f32_16x16x32_bf16 v[6:9], v[196:199], v[236:239], v[6:9]
	v_mfma_f32_16x16x32_bf16 v[2:5], v[204:207], v[236:239], v[2:5]
	v_mfma_f32_16x16x32_bf16 v[30:33], v[200:203], v[216:219], v[30:33]
	v_mfma_f32_16x16x32_bf16 v[26:29], v[208:211], v[216:219], v[26:29]
	v_mfma_f32_16x16x32_bf16 v[22:25], v[200:203], v[224:227], v[22:25]
	v_mfma_f32_16x16x32_bf16 v[18:21], v[208:211], v[224:227], v[18:21]
	v_mfma_f32_16x16x32_bf16 v[14:17], v[200:203], v[232:235], v[14:17]
	v_mfma_f32_16x16x32_bf16 v[10:13], v[208:211], v[232:235], v[10:13]
	v_mfma_f32_16x16x32_bf16 v[6:9], v[200:203], v[240:243], v[6:9]
	v_mfma_f32_16x16x32_bf16 v[2:5], v[208:211], v[240:243], v[2:5]
	s_setprio 0
	s_barrier
	s_add_u32 s12, s12, 0x100
	s_addc_u32 s13, s13, 0
	s_add_u32 s2, s2, 0x100
	s_addc_u32 s11, s11, 0
	s_cmp_ge_u32 s18, s81
	s_mov_b32 s14, s18
	s_cbranch_scc0 .LBB0_154
	s_and_b64 vcc, exec, s[56:57]
	s_cbranch_vccz .LBB0_157
	s_barrier
